# dn GEMM EpiResid epilogue: de-serialised RMW chain (x loads software-pipelined via SADDR offsets, stats/gate/lg/lb loads batched)
# speedup vs baseline: 1.0162x; 1.0130x over previous
.Ldnt_epi:
	v_or_b32_e32 v130, s4, v1
	v_add_u32_e32 v130, s62, v130
	v_cndmask_b32_e64 v131, 0, 1, s[14:15]
	v_cmp_ne_u32_e64 s[4:5], 1, v131
	v_ashrrev_i32_e32 v131, 31, v130
	s_lshl_b64 s[26:27], s[26:27], 2
	v_lshl_or_b32 v220, s2, 8, v236
	s_add_u32 s26, s18, s26
	v_ashrrev_i32_e32 v221, 31, v220
	s_addc_u32 s27, s41, s27
	v_lshl_add_u64 v[202:203], v[220:221], 2, s[26:27]
	v_lshlrev_b64 v[200:201], 2, v[220:221]
	v_lshl_add_u64 v[198:199], s[12:13], 0, v[200:201]
	v_lshl_add_u64 v[200:201], s[10:11], 0, v[200:201]
	v_mov_b32_e32 v194, 0
	v_mov_b32_e32 v196, 1.0
	v_mov_b32_e32 v184, 0
	v_mov_b32_e32 v182, 1.0
	v_mov_b32_e32 v186, 0
	v_mov_b32_e32 v192, 1.0
	v_mov_b32_e32 v176, 0
	v_mov_b32_e32 v174, 1.0
	v_mov_b32_e32 v178, 0
	v_mov_b32_e32 v180, 1.0
	v_mov_b32_e32 v168, 0
	v_mov_b32_e32 v166, 1.0
	v_mov_b32_e32 v170, 0
	v_mov_b32_e32 v172, 1.0
	v_mov_b32_e32 v162, 0
	v_mov_b32_e32 v164, 1.0
	s_andn2_b64 vcc, exec, s[14:15]
	s_cbranch_vccnz .Ldne_nostats
	v_lshl_add_u64 v[132:133], v[130:131], 3, s[68:69]
	global_load_dwordx2 v[194:195], v[132:133], off
	global_load_dwordx2 v[184:185], v[132:133], off offset:128
	global_load_dwordx2 v[186:187], v[132:133], off offset:256
	global_load_dwordx2 v[176:177], v[132:133], off offset:384
	global_load_dwordx2 v[178:179], v[132:133], off offset:1024
	global_load_dwordx2 v[168:169], v[132:133], off offset:1152
	global_load_dwordx2 v[170:171], v[132:133], off offset:1280
	global_load_dwordx2 v[162:163], v[132:133], off offset:1408
.Ldne_nostats:
	v_cndmask_b32_e64 v198, v198, v202, s[4:5]
	v_cndmask_b32_e64 v199, v199, v203, s[4:5]
	v_cndmask_b32_e64 v200, v200, v202, s[4:5]
	v_cndmask_b32_e64 v201, v201, v203, s[4:5]
	global_load_dwordx4 v[216:219], v[202:203], off
	global_load_dwordx4 v[208:211], v[200:201], off
	global_load_dwordx4 v[212:215], v[198:199], off
	v_add_lshl_u32 v165, v142, v220, 2
	v_add_lshl_u32 v167, v146, v220, 2
	v_add_lshl_u32 v173, v148, v220, 2
	v_add_lshl_u32 v175, v150, v220, 2
	v_add_lshl_u32 v181, v144, v220, 2
	v_add_lshl_u32 v183, v152, v220, 2
	v_add_lshl_u32 v193, v154, v220, 2
	v_add_lshl_u32 v197, v156, v220, 2
	global_load_dwordx4 v[238:241], v165, s[24:25]
	global_load_dwordx4 v[242:245], v167, s[24:25]
	global_load_dwordx4 v[130:133], v173, s[24:25]
	global_load_dwordx4 v[204:207], v175, s[24:25]
	s_waitcnt vmcnt(7)
	s_andn2_b64 vcc, exec, s[14:15]
	s_cbranch_vccnz .Ldne_nomov
	v_mov_b32_e32 v196, v195
	v_mov_b32_e32 v182, v185
	v_mov_b32_e32 v192, v187
	v_mov_b32_e32 v174, v177
	v_mov_b32_e32 v180, v179
	v_mov_b32_e32 v166, v169
	v_mov_b32_e32 v172, v171
	v_mov_b32_e32 v164, v163
.Ldne_nomov:
	s_waitcnt vmcnt(4)
	v_pk_mul_f32 v[216:217], v[216:217], 0.5 op_sel_hi:[1,0]
	v_pk_mul_f32 v[218:219], v[218:219], 0.5 op_sel_hi:[1,0]
	s_and_b64 vcc, exec, s[4:5]
	s_cbranch_vccnz .Ldne_pid0
	v_pk_mul_f32 v[208:209], v[208:209], s[54:55] op_sel_hi:[1,0]
	v_pk_mul_f32 v[210:211], v[210:211], s[54:55] op_sel_hi:[1,0]
	v_pk_mul_f32 v[212:213], v[212:213], s[54:55] op_sel_hi:[1,0]
	v_pk_mul_f32 v[214:215], v[214:215], s[54:55] op_sel_hi:[1,0]
	s_branch .Ldne_pdn0
.Ldne_pid0:
	v_mov_b32_e32 v208, 0x3fb504f3
	v_mov_b32_e32 v209, 0x3fb504f3
	v_mov_b32_e32 v210, 0x3fb504f3
	v_mov_b32_e32 v211, 0x3fb504f3
	v_mov_b32_e32 v212, 0
	v_mov_b32_e32 v213, 0
	v_mov_b32_e32 v214, 0
	v_mov_b32_e32 v215, 0
.Ldne_pdn0:
	s_waitcnt vmcnt(3)
	v_sub_f32_e32 v239, v239, v194
	v_sub_f32_e32 v238, v238, v194
	v_sub_f32_e32 v241, v241, v194
	v_sub_f32_e32 v240, v240, v194
	v_pk_mul_f32 v[240:241], v[196:197], v[240:241] op_sel_hi:[0,1]
	v_pk_mul_f32 v[238:239], v[196:197], v[238:239] op_sel_hi:[0,1]
	v_pk_fma_f32 v[238:239], v[208:209], v[238:239], v[212:213]
	v_pk_fma_f32 v[240:241], v[210:211], v[240:241], v[214:215]
	v_pk_fma_f32 v[126:127], v[126:127], v[216:217], v[238:239]
	v_pk_fma_f32 v[128:129], v[128:129], v[218:219], v[240:241]
	global_store_dwordx4 v165, v[126:129], s[96:97]
	global_load_dwordx4 v[238:241], v181, s[24:25]
	global_load_dwordx4 v[126:129], v183, s[24:25]
	s_waitcnt vmcnt(5)
	v_sub_f32_e32 v243, v243, v184
	v_sub_f32_e32 v242, v242, v184
	v_sub_f32_e32 v245, v245, v184
	v_sub_f32_e32 v244, v244, v184
	v_pk_mul_f32 v[244:245], v[182:183], v[244:245] op_sel_hi:[0,1]
	v_pk_mul_f32 v[242:243], v[182:183], v[242:243] op_sel_hi:[0,1]
	v_pk_fma_f32 v[242:243], v[208:209], v[242:243], v[212:213]
	v_pk_fma_f32 v[244:245], v[210:211], v[244:245], v[214:215]
	v_pk_fma_f32 v[122:123], v[122:123], v[216:217], v[242:243]
	v_pk_fma_f32 v[124:125], v[124:125], v[218:219], v[244:245]
	global_store_dwordx4 v167, v[122:125], s[96:97]
	global_load_dwordx4 v[242:245], v193, s[24:25]
	global_load_dwordx4 v[122:125], v197, s[24:25]
	s_waitcnt vmcnt(7)
	v_sub_f32_e32 v131, v131, v186
	v_sub_f32_e32 v130, v130, v186
	v_sub_f32_e32 v133, v133, v186
	v_sub_f32_e32 v132, v132, v186
	v_pk_mul_f32 v[132:133], v[192:193], v[132:133] op_sel_hi:[0,1]
	v_pk_mul_f32 v[130:131], v[192:193], v[130:131] op_sel_hi:[0,1]
	v_pk_fma_f32 v[130:131], v[208:209], v[130:131], v[212:213]
	v_pk_fma_f32 v[132:133], v[210:211], v[132:133], v[214:215]
	v_pk_fma_f32 v[118:119], v[118:119], v[216:217], v[130:131]
	v_pk_fma_f32 v[120:121], v[120:121], v[218:219], v[132:133]
	global_store_dwordx4 v173, v[118:121], s[96:97]
	s_waitcnt vmcnt(7)
	v_sub_f32_e32 v205, v205, v176
	v_sub_f32_e32 v204, v204, v176
	v_sub_f32_e32 v207, v207, v176
	v_sub_f32_e32 v206, v206, v176
	v_pk_mul_f32 v[206:207], v[174:175], v[206:207] op_sel_hi:[0,1]
	v_pk_mul_f32 v[204:205], v[174:175], v[204:205] op_sel_hi:[0,1]
	v_pk_fma_f32 v[204:205], v[208:209], v[204:205], v[212:213]
	v_pk_fma_f32 v[206:207], v[210:211], v[206:207], v[214:215]
	v_pk_fma_f32 v[114:115], v[114:115], v[216:217], v[204:205]
	v_pk_fma_f32 v[116:117], v[116:117], v[218:219], v[206:207]
	global_store_dwordx4 v175, v[114:117], s[96:97]
	global_load_dwordx4 v[130:133], v[202:203], off offset:16
	global_load_dwordx4 v[118:121], v[200:201], off offset:16
	global_load_dwordx4 v[204:207], v[198:199], off offset:16
	global_load_dwordx4 v[114:117], v165, s[24:25] offset:16
	s_waitcnt vmcnt(10)
	v_sub_f32_e32 v239, v239, v178
	v_sub_f32_e32 v238, v238, v178
	v_sub_f32_e32 v241, v241, v178
	v_sub_f32_e32 v240, v240, v178
	v_pk_mul_f32 v[240:241], v[180:181], v[240:241] op_sel_hi:[0,1]
	v_pk_mul_f32 v[238:239], v[180:181], v[238:239] op_sel_hi:[0,1]
	v_pk_fma_f32 v[238:239], v[208:209], v[238:239], v[212:213]
	v_pk_fma_f32 v[240:241], v[210:211], v[240:241], v[214:215]
	v_pk_fma_f32 v[110:111], v[110:111], v[216:217], v[238:239]
	v_pk_fma_f32 v[112:113], v[112:113], v[218:219], v[240:241]
	global_store_dwordx4 v181, v[110:113], s[96:97]
	global_load_dwordx4 v[238:241], v167, s[24:25] offset:16
	global_load_dwordx4 v[110:113], v173, s[24:25] offset:16
	s_waitcnt vmcnt(12)
	v_sub_f32_e32 v127, v127, v168
	v_sub_f32_e32 v126, v126, v168
	v_sub_f32_e32 v129, v129, v168
	v_sub_f32_e32 v128, v128, v168
	v_pk_mul_f32 v[128:129], v[166:167], v[128:129] op_sel_hi:[0,1]
	v_pk_mul_f32 v[126:127], v[166:167], v[126:127] op_sel_hi:[0,1]
	v_pk_fma_f32 v[126:127], v[208:209], v[126:127], v[212:213]
	v_pk_fma_f32 v[128:129], v[210:211], v[128:129], v[214:215]
	v_pk_fma_f32 v[106:107], v[106:107], v[216:217], v[126:127]
	v_pk_fma_f32 v[108:109], v[108:109], v[218:219], v[128:129]
	global_store_dwordx4 v183, v[106:109], s[96:97]
	global_load_dwordx4 v[126:129], v175, s[24:25] offset:16
	global_load_dwordx4 v[106:109], v181, s[24:25] offset:16
	s_waitcnt vmcnt(13)
	v_sub_f32_e32 v243, v243, v170
	v_sub_f32_e32 v242, v242, v170
	v_sub_f32_e32 v245, v245, v170
	v_sub_f32_e32 v244, v244, v170
	v_pk_mul_f32 v[244:245], v[172:173], v[244:245] op_sel_hi:[0,1]
	v_pk_mul_f32 v[242:243], v[172:173], v[242:243] op_sel_hi:[0,1]
	v_pk_fma_f32 v[242:243], v[208:209], v[242:243], v[212:213]
	v_pk_fma_f32 v[244:245], v[210:211], v[244:245], v[214:215]
	v_pk_fma_f32 v[102:103], v[102:103], v[216:217], v[242:243]
	v_pk_fma_f32 v[104:105], v[104:105], v[218:219], v[244:245]
	global_store_dwordx4 v193, v[102:105], s[96:97]
	global_load_dwordx4 v[242:245], v183, s[24:25] offset:16
	global_load_dwordx4 v[102:105], v193, s[24:25] offset:16
	s_waitcnt vmcnt(15)
	v_sub_f32_e32 v123, v123, v162
	v_sub_f32_e32 v122, v122, v162
	v_sub_f32_e32 v125, v125, v162
	v_sub_f32_e32 v124, v124, v162
	v_pk_mul_f32 v[124:125], v[164:165], v[124:125] op_sel_hi:[0,1]
	v_pk_mul_f32 v[122:123], v[164:165], v[122:123] op_sel_hi:[0,1]
	v_pk_fma_f32 v[122:123], v[208:209], v[122:123], v[212:213]
	v_pk_fma_f32 v[124:125], v[210:211], v[124:125], v[214:215]
	v_pk_fma_f32 v[98:99], v[98:99], v[216:217], v[122:123]
	v_pk_fma_f32 v[100:101], v[100:101], v[218:219], v[124:125]
	global_store_dwordx4 v197, v[98:101], s[96:97]
	global_load_dwordx4 v[122:125], v197, s[24:25] offset:16
	global_load_dwordx4 v[98:101], v[202:203], off offset:512
	global_load_dwordx4 v[216:219], v[200:201], off offset:512
	global_load_dwordx4 v[208:211], v[198:199], off offset:512
	global_load_dwordx4 v[212:215], v165, s[24:25] offset:512
	s_waitcnt vmcnt(16)
	v_pk_mul_f32 v[130:131], v[130:131], 0.5 op_sel_hi:[1,0]
	v_pk_mul_f32 v[132:133], v[132:133], 0.5 op_sel_hi:[1,0]
	s_and_b64 vcc, exec, s[4:5]
	s_cbranch_vccnz .Ldne_pid1
	v_pk_mul_f32 v[118:119], v[118:119], s[54:55] op_sel_hi:[1,0]
	v_pk_mul_f32 v[120:121], v[120:121], s[54:55] op_sel_hi:[1,0]
	v_pk_mul_f32 v[204:205], v[204:205], s[54:55] op_sel_hi:[1,0]
	v_pk_mul_f32 v[206:207], v[206:207], s[54:55] op_sel_hi:[1,0]
	s_branch .Ldne_pdn1
.Ldne_pid1:
	v_mov_b32_e32 v118, 0x3fb504f3
	v_mov_b32_e32 v119, 0x3fb504f3
	v_mov_b32_e32 v120, 0x3fb504f3
	v_mov_b32_e32 v121, 0x3fb504f3
	v_mov_b32_e32 v204, 0
	v_mov_b32_e32 v205, 0
	v_mov_b32_e32 v206, 0
	v_mov_b32_e32 v207, 0
.Ldne_pdn1:
	s_waitcnt vmcnt(15)
	v_sub_f32_e32 v115, v115, v194
	v_sub_f32_e32 v114, v114, v194
	v_sub_f32_e32 v117, v117, v194
	v_sub_f32_e32 v116, v116, v194
	v_pk_mul_f32 v[116:117], v[196:197], v[116:117] op_sel_hi:[0,1]
	v_pk_mul_f32 v[114:115], v[196:197], v[114:115] op_sel_hi:[0,1]
	v_pk_fma_f32 v[114:115], v[118:119], v[114:115], v[204:205]
	v_pk_fma_f32 v[116:117], v[120:121], v[116:117], v[206:207]
	v_pk_fma_f32 v[94:95], v[94:95], v[130:131], v[114:115]
	v_pk_fma_f32 v[96:97], v[96:97], v[132:133], v[116:117]
	global_store_dwordx4 v165, v[94:97], s[96:97] offset:16
	global_load_dwordx4 v[114:117], v167, s[24:25] offset:512
	global_load_dwordx4 v[94:97], v173, s[24:25] offset:512
	s_waitcnt vmcnt(16)
	v_sub_f32_e32 v239, v239, v184
	v_sub_f32_e32 v238, v238, v184
	v_sub_f32_e32 v241, v241, v184
	v_sub_f32_e32 v240, v240, v184
	v_pk_mul_f32 v[240:241], v[182:183], v[240:241] op_sel_hi:[0,1]
	v_pk_mul_f32 v[238:239], v[182:183], v[238:239] op_sel_hi:[0,1]
	v_pk_fma_f32 v[238:239], v[118:119], v[238:239], v[204:205]
	v_pk_fma_f32 v[240:241], v[120:121], v[240:241], v[206:207]
	v_pk_fma_f32 v[90:91], v[90:91], v[130:131], v[238:239]
	v_pk_fma_f32 v[92:93], v[92:93], v[132:133], v[240:241]
	global_store_dwordx4 v167, v[90:93], s[96:97] offset:16
	global_load_dwordx4 v[238:241], v175, s[24:25] offset:512
	global_load_dwordx4 v[90:93], v181, s[24:25] offset:512
	s_waitcnt vmcnt(18)
	v_sub_f32_e32 v111, v111, v186
	v_sub_f32_e32 v110, v110, v186
	v_sub_f32_e32 v113, v113, v186
	v_sub_f32_e32 v112, v112, v186
	v_pk_mul_f32 v[112:113], v[192:193], v[112:113] op_sel_hi:[0,1]
	v_pk_mul_f32 v[110:111], v[192:193], v[110:111] op_sel_hi:[0,1]
	v_pk_fma_f32 v[110:111], v[118:119], v[110:111], v[204:205]
	v_pk_fma_f32 v[112:113], v[120:121], v[112:113], v[206:207]
	v_pk_fma_f32 v[86:87], v[86:87], v[130:131], v[110:111]
	v_pk_fma_f32 v[88:89], v[88:89], v[132:133], v[112:113]
	global_store_dwordx4 v173, v[86:89], s[96:97] offset:16
	global_load_dwordx4 v[110:113], v183, s[24:25] offset:512
	global_load_dwordx4 v[86:89], v193, s[24:25] offset:512
	s_waitcnt vmcnt(19)
	v_sub_f32_e32 v127, v127, v176
	v_sub_f32_e32 v126, v126, v176
	v_sub_f32_e32 v129, v129, v176
	v_sub_f32_e32 v128, v128, v176
	v_pk_mul_f32 v[128:129], v[174:175], v[128:129] op_sel_hi:[0,1]
	v_pk_mul_f32 v[126:127], v[174:175], v[126:127] op_sel_hi:[0,1]
	v_pk_fma_f32 v[126:127], v[118:119], v[126:127], v[204:205]
	v_pk_fma_f32 v[128:129], v[120:121], v[128:129], v[206:207]
	v_pk_fma_f32 v[82:83], v[82:83], v[130:131], v[126:127]
	v_pk_fma_f32 v[84:85], v[84:85], v[132:133], v[128:129]
	global_store_dwordx4 v175, v[82:85], s[96:97] offset:16
	global_load_dwordx4 v[126:129], v197, s[24:25] offset:512
	s_waitcnt vmcnt(20)
	v_sub_f32_e32 v107, v107, v178
	v_sub_f32_e32 v106, v106, v178
	v_sub_f32_e32 v109, v109, v178
	v_sub_f32_e32 v108, v108, v178
	v_pk_mul_f32 v[108:109], v[180:181], v[108:109] op_sel_hi:[0,1]
	v_pk_mul_f32 v[106:107], v[180:181], v[106:107] op_sel_hi:[0,1]
	v_pk_fma_f32 v[106:107], v[118:119], v[106:107], v[204:205]
	v_pk_fma_f32 v[108:109], v[120:121], v[108:109], v[206:207]
	v_pk_fma_f32 v[78:79], v[78:79], v[130:131], v[106:107]
	v_pk_fma_f32 v[80:81], v[80:81], v[132:133], v[108:109]
	global_store_dwordx4 v181, v[78:81], s[96:97] offset:16
	global_load_dwordx4 v[82:85], v[202:203], off offset:528
	global_load_dwordx4 v[106:109], v[200:201], off offset:528
	global_load_dwordx4 v[78:81], v[198:199], off offset:528
	s_waitcnt vmcnt(22)
	v_sub_f32_e32 v243, v243, v168
	v_sub_f32_e32 v242, v242, v168
	v_sub_f32_e32 v245, v245, v168
	v_sub_f32_e32 v244, v244, v168
	v_pk_mul_f32 v[244:245], v[166:167], v[244:245] op_sel_hi:[0,1]
	v_pk_mul_f32 v[242:243], v[166:167], v[242:243] op_sel_hi:[0,1]
	v_pk_fma_f32 v[242:243], v[118:119], v[242:243], v[204:205]
	v_pk_fma_f32 v[244:245], v[120:121], v[244:245], v[206:207]
	v_pk_fma_f32 v[74:75], v[74:75], v[130:131], v[242:243]
	v_pk_fma_f32 v[76:77], v[76:77], v[132:133], v[244:245]
	global_store_dwordx4 v183, v[74:77], s[96:97] offset:16
	global_load_dwordx4 v[242:245], v165, s[24:25] offset:528
	global_load_dwordx4 v[74:77], v167, s[24:25] offset:528
	s_waitcnt vmcnt(24)
	v_sub_f32_e32 v103, v103, v170
	v_sub_f32_e32 v102, v102, v170
	v_sub_f32_e32 v105, v105, v170
	v_sub_f32_e32 v104, v104, v170
	v_pk_mul_f32 v[104:105], v[172:173], v[104:105] op_sel_hi:[0,1]
	v_pk_mul_f32 v[102:103], v[172:173], v[102:103] op_sel_hi:[0,1]
	v_pk_fma_f32 v[102:103], v[118:119], v[102:103], v[204:205]
	v_pk_fma_f32 v[104:105], v[120:121], v[104:105], v[206:207]
	v_pk_fma_f32 v[70:71], v[70:71], v[130:131], v[102:103]
	v_pk_fma_f32 v[72:73], v[72:73], v[132:133], v[104:105]
	global_store_dwordx4 v193, v[70:73], s[96:97] offset:16
	global_load_dwordx4 v[102:105], v173, s[24:25] offset:528
	global_load_dwordx4 v[70:73], v175, s[24:25] offset:528
	s_waitcnt vmcnt(25)
	v_sub_f32_e32 v123, v123, v162
	v_sub_f32_e32 v122, v122, v162
	v_sub_f32_e32 v125, v125, v162
	v_sub_f32_e32 v124, v124, v162
	v_pk_mul_f32 v[124:125], v[164:165], v[124:125] op_sel_hi:[0,1]
	v_pk_mul_f32 v[122:123], v[164:165], v[122:123] op_sel_hi:[0,1]
	v_pk_fma_f32 v[122:123], v[118:119], v[122:123], v[204:205]
	v_pk_fma_f32 v[124:125], v[120:121], v[124:125], v[206:207]
	v_pk_fma_f32 v[66:67], v[66:67], v[130:131], v[122:123]
	v_pk_fma_f32 v[68:69], v[68:69], v[132:133], v[124:125]
	global_store_dwordx4 v197, v[66:69], s[96:97] offset:16
	global_load_dwordx4 v[122:125], v181, s[24:25] offset:528
	global_load_dwordx4 v[66:69], v183, s[24:25] offset:528
	global_load_dwordx4 v[130:133], v193, s[24:25] offset:528
	global_load_dwordx4 v[118:121], v197, s[24:25] offset:528
	s_waitcnt vmcnt(27)
	v_pk_mul_f32 v[98:99], v[98:99], 0.5 op_sel_hi:[1,0]
	v_pk_mul_f32 v[100:101], v[100:101], 0.5 op_sel_hi:[1,0]
	s_and_b64 vcc, exec, s[4:5]
	s_cbranch_vccnz .Ldne_pid2
	v_pk_mul_f32 v[216:217], v[216:217], s[54:55] op_sel_hi:[1,0]
	v_pk_mul_f32 v[218:219], v[218:219], s[54:55] op_sel_hi:[1,0]
	v_pk_mul_f32 v[208:209], v[208:209], s[54:55] op_sel_hi:[1,0]
	v_pk_mul_f32 v[210:211], v[210:211], s[54:55] op_sel_hi:[1,0]
	s_branch .Ldne_pdn2
.Ldne_pid2:
	v_mov_b32_e32 v216, 0x3fb504f3
	v_mov_b32_e32 v217, 0x3fb504f3
	v_mov_b32_e32 v218, 0x3fb504f3
	v_mov_b32_e32 v219, 0x3fb504f3
	v_mov_b32_e32 v208, 0
	v_mov_b32_e32 v209, 0
	v_mov_b32_e32 v210, 0
	v_mov_b32_e32 v211, 0
.Ldne_pdn2:
	s_waitcnt vmcnt(26)
	v_sub_f32_e32 v213, v213, v194
	v_sub_f32_e32 v212, v212, v194
	v_sub_f32_e32 v215, v215, v194
	v_sub_f32_e32 v214, v214, v194
	v_pk_mul_f32 v[214:215], v[196:197], v[214:215] op_sel_hi:[0,1]
	v_pk_mul_f32 v[212:213], v[196:197], v[212:213] op_sel_hi:[0,1]
	v_pk_fma_f32 v[212:213], v[216:217], v[212:213], v[208:209]
	v_pk_fma_f32 v[214:215], v[218:219], v[214:215], v[210:211]
	v_pk_fma_f32 v[62:63], v[62:63], v[98:99], v[212:213]
	v_pk_fma_f32 v[64:65], v[64:65], v[100:101], v[214:215]
	global_store_dwordx4 v165, v[62:65], s[96:97] offset:512
	s_waitcnt vmcnt(25)
	v_sub_f32_e32 v115, v115, v184
	v_sub_f32_e32 v114, v114, v184
	v_sub_f32_e32 v117, v117, v184
	v_sub_f32_e32 v116, v116, v184
	v_pk_mul_f32 v[116:117], v[182:183], v[116:117] op_sel_hi:[0,1]
	v_pk_mul_f32 v[114:115], v[182:183], v[114:115] op_sel_hi:[0,1]
	v_pk_fma_f32 v[114:115], v[216:217], v[114:115], v[208:209]
	v_pk_fma_f32 v[116:117], v[218:219], v[116:117], v[210:211]
	v_pk_fma_f32 v[58:59], v[58:59], v[98:99], v[114:115]
	v_pk_fma_f32 v[60:61], v[60:61], v[100:101], v[116:117]
	global_store_dwordx4 v167, v[58:61], s[96:97] offset:512
	s_waitcnt vmcnt(25)
	v_sub_f32_e32 v95, v95, v186
	v_sub_f32_e32 v94, v94, v186
	v_sub_f32_e32 v97, v97, v186
	v_sub_f32_e32 v96, v96, v186
	v_pk_mul_f32 v[96:97], v[192:193], v[96:97] op_sel_hi:[0,1]
	v_pk_mul_f32 v[94:95], v[192:193], v[94:95] op_sel_hi:[0,1]
	v_pk_fma_f32 v[94:95], v[216:217], v[94:95], v[208:209]
	v_pk_fma_f32 v[96:97], v[218:219], v[96:97], v[210:211]
	v_pk_fma_f32 v[54:55], v[54:55], v[98:99], v[94:95]
	v_pk_fma_f32 v[56:57], v[56:57], v[100:101], v[96:97]
	global_store_dwordx4 v173, v[54:57], s[96:97] offset:512
	s_waitcnt vmcnt(24)
	v_sub_f32_e32 v239, v239, v176
	v_sub_f32_e32 v238, v238, v176
	v_sub_f32_e32 v241, v241, v176
	v_sub_f32_e32 v240, v240, v176
	v_pk_mul_f32 v[240:241], v[174:175], v[240:241] op_sel_hi:[0,1]
	v_pk_mul_f32 v[238:239], v[174:175], v[238:239] op_sel_hi:[0,1]
	v_pk_fma_f32 v[238:239], v[216:217], v[238:239], v[208:209]
	v_pk_fma_f32 v[240:241], v[218:219], v[240:241], v[210:211]
	v_pk_fma_f32 v[50:51], v[50:51], v[98:99], v[238:239]
	v_pk_fma_f32 v[52:53], v[52:53], v[100:101], v[240:241]
	global_store_dwordx4 v175, v[50:53], s[96:97] offset:512
	s_waitcnt vmcnt(24)
	v_sub_f32_e32 v91, v91, v178
	v_sub_f32_e32 v90, v90, v178
	v_sub_f32_e32 v93, v93, v178
	v_sub_f32_e32 v92, v92, v178
	v_pk_mul_f32 v[92:93], v[180:181], v[92:93] op_sel_hi:[0,1]
	v_pk_mul_f32 v[90:91], v[180:181], v[90:91] op_sel_hi:[0,1]
	v_pk_fma_f32 v[90:91], v[216:217], v[90:91], v[208:209]
	v_pk_fma_f32 v[92:93], v[218:219], v[92:93], v[210:211]
	v_pk_fma_f32 v[46:47], v[46:47], v[98:99], v[90:91]
	v_pk_fma_f32 v[48:49], v[48:49], v[100:101], v[92:93]
	global_store_dwordx4 v181, v[46:49], s[96:97] offset:512
	s_waitcnt vmcnt(23)
	v_sub_f32_e32 v111, v111, v168
	v_sub_f32_e32 v110, v110, v168
	v_sub_f32_e32 v113, v113, v168
	v_sub_f32_e32 v112, v112, v168
	v_pk_mul_f32 v[112:113], v[166:167], v[112:113] op_sel_hi:[0,1]
	v_pk_mul_f32 v[110:111], v[166:167], v[110:111] op_sel_hi:[0,1]
	v_pk_fma_f32 v[110:111], v[216:217], v[110:111], v[208:209]
	v_pk_fma_f32 v[112:113], v[218:219], v[112:113], v[210:211]
	v_pk_fma_f32 v[42:43], v[42:43], v[98:99], v[110:111]
	v_pk_fma_f32 v[44:45], v[44:45], v[100:101], v[112:113]
	global_store_dwordx4 v183, v[42:45], s[96:97] offset:512
	s_waitcnt vmcnt(23)
	v_sub_f32_e32 v87, v87, v170
	v_sub_f32_e32 v86, v86, v170
	v_sub_f32_e32 v89, v89, v170
	v_sub_f32_e32 v88, v88, v170
	v_pk_mul_f32 v[88:89], v[172:173], v[88:89] op_sel_hi:[0,1]
	v_pk_mul_f32 v[86:87], v[172:173], v[86:87] op_sel_hi:[0,1]
	v_pk_fma_f32 v[86:87], v[216:217], v[86:87], v[208:209]
	v_pk_fma_f32 v[88:89], v[218:219], v[88:89], v[210:211]
	v_pk_fma_f32 v[38:39], v[38:39], v[98:99], v[86:87]
	v_pk_fma_f32 v[40:41], v[40:41], v[100:101], v[88:89]
	global_store_dwordx4 v193, v[38:41], s[96:97] offset:512
	s_waitcnt vmcnt(22)
	v_sub_f32_e32 v127, v127, v162
	v_sub_f32_e32 v126, v126, v162
	v_sub_f32_e32 v129, v129, v162
	v_sub_f32_e32 v128, v128, v162
	v_pk_mul_f32 v[128:129], v[164:165], v[128:129] op_sel_hi:[0,1]
	v_pk_mul_f32 v[126:127], v[164:165], v[126:127] op_sel_hi:[0,1]
	v_pk_fma_f32 v[126:127], v[216:217], v[126:127], v[208:209]
	v_pk_fma_f32 v[128:129], v[218:219], v[128:129], v[210:211]
	v_pk_fma_f32 v[34:35], v[34:35], v[98:99], v[126:127]
	v_pk_fma_f32 v[36:37], v[36:37], v[100:101], v[128:129]
	global_store_dwordx4 v197, v[34:37], s[96:97] offset:512
	s_waitcnt vmcnt(19)
	v_pk_mul_f32 v[82:83], v[82:83], 0.5 op_sel_hi:[1,0]
	v_pk_mul_f32 v[84:85], v[84:85], 0.5 op_sel_hi:[1,0]
	s_and_b64 vcc, exec, s[4:5]
	s_cbranch_vccnz .Ldne_pid3
	v_pk_mul_f32 v[106:107], v[106:107], s[54:55] op_sel_hi:[1,0]
	v_pk_mul_f32 v[108:109], v[108:109], s[54:55] op_sel_hi:[1,0]
	v_pk_mul_f32 v[78:79], v[78:79], s[54:55] op_sel_hi:[1,0]
	v_pk_mul_f32 v[80:81], v[80:81], s[54:55] op_sel_hi:[1,0]
	s_branch .Ldne_pdn3
.Ldne_pid3:
	v_mov_b32_e32 v106, 0x3fb504f3
	v_mov_b32_e32 v107, 0x3fb504f3
	v_mov_b32_e32 v108, 0x3fb504f3
	v_mov_b32_e32 v109, 0x3fb504f3
	v_mov_b32_e32 v78, 0
	v_mov_b32_e32 v79, 0
	v_mov_b32_e32 v80, 0
	v_mov_b32_e32 v81, 0
.Ldne_pdn3:
	s_waitcnt vmcnt(17)
	v_sub_f32_e32 v243, v243, v194
	v_sub_f32_e32 v242, v242, v194
	v_sub_f32_e32 v245, v245, v194
	v_sub_f32_e32 v244, v244, v194
	v_pk_mul_f32 v[244:245], v[196:197], v[244:245] op_sel_hi:[0,1]
	v_pk_mul_f32 v[242:243], v[196:197], v[242:243] op_sel_hi:[0,1]
	v_pk_fma_f32 v[242:243], v[106:107], v[242:243], v[78:79]
	v_pk_fma_f32 v[244:245], v[108:109], v[244:245], v[80:81]
	v_pk_fma_f32 v[30:31], v[30:31], v[82:83], v[242:243]
	v_pk_fma_f32 v[32:33], v[32:33], v[84:85], v[244:245]
	global_store_dwordx4 v165, v[30:33], s[96:97] offset:528
	s_waitcnt vmcnt(17)
	v_sub_f32_e32 v75, v75, v184
	v_sub_f32_e32 v74, v74, v184
	v_sub_f32_e32 v77, v77, v184
	v_sub_f32_e32 v76, v76, v184
	v_pk_mul_f32 v[76:77], v[182:183], v[76:77] op_sel_hi:[0,1]
	v_pk_mul_f32 v[74:75], v[182:183], v[74:75] op_sel_hi:[0,1]
	v_pk_fma_f32 v[74:75], v[106:107], v[74:75], v[78:79]
	v_pk_fma_f32 v[76:77], v[108:109], v[76:77], v[80:81]
	v_pk_fma_f32 v[26:27], v[26:27], v[82:83], v[74:75]
	v_pk_fma_f32 v[28:29], v[28:29], v[84:85], v[76:77]
	global_store_dwordx4 v167, v[26:29], s[96:97] offset:528
	s_waitcnt vmcnt(16)
	v_sub_f32_e32 v103, v103, v186
	v_sub_f32_e32 v102, v102, v186
	v_sub_f32_e32 v105, v105, v186
	v_sub_f32_e32 v104, v104, v186
	v_pk_mul_f32 v[104:105], v[192:193], v[104:105] op_sel_hi:[0,1]
	v_pk_mul_f32 v[102:103], v[192:193], v[102:103] op_sel_hi:[0,1]
	v_pk_fma_f32 v[102:103], v[106:107], v[102:103], v[78:79]
	v_pk_fma_f32 v[104:105], v[108:109], v[104:105], v[80:81]
	v_pk_fma_f32 v[22:23], v[22:23], v[82:83], v[102:103]
	v_pk_fma_f32 v[24:25], v[24:25], v[84:85], v[104:105]
	global_store_dwordx4 v173, v[22:25], s[96:97] offset:528
	s_waitcnt vmcnt(16)
	v_sub_f32_e32 v71, v71, v176
	v_sub_f32_e32 v70, v70, v176
	v_sub_f32_e32 v73, v73, v176
	v_sub_f32_e32 v72, v72, v176
	v_pk_mul_f32 v[72:73], v[174:175], v[72:73] op_sel_hi:[0,1]
	v_pk_mul_f32 v[70:71], v[174:175], v[70:71] op_sel_hi:[0,1]
	v_pk_fma_f32 v[70:71], v[106:107], v[70:71], v[78:79]
	v_pk_fma_f32 v[72:73], v[108:109], v[72:73], v[80:81]
	v_pk_fma_f32 v[18:19], v[18:19], v[82:83], v[70:71]
	v_pk_fma_f32 v[20:21], v[20:21], v[84:85], v[72:73]
	global_store_dwordx4 v175, v[18:21], s[96:97] offset:528
	s_waitcnt vmcnt(15)
	v_sub_f32_e32 v123, v123, v178
	v_sub_f32_e32 v122, v122, v178
	v_sub_f32_e32 v125, v125, v178
	v_sub_f32_e32 v124, v124, v178
	v_pk_mul_f32 v[124:125], v[180:181], v[124:125] op_sel_hi:[0,1]
	v_pk_mul_f32 v[122:123], v[180:181], v[122:123] op_sel_hi:[0,1]
	v_pk_fma_f32 v[122:123], v[106:107], v[122:123], v[78:79]
	v_pk_fma_f32 v[124:125], v[108:109], v[124:125], v[80:81]
	v_pk_fma_f32 v[14:15], v[14:15], v[82:83], v[122:123]
	v_pk_fma_f32 v[16:17], v[16:17], v[84:85], v[124:125]
	global_store_dwordx4 v181, v[14:17], s[96:97] offset:528
	s_waitcnt vmcnt(15)
	v_sub_f32_e32 v67, v67, v168
	v_sub_f32_e32 v66, v66, v168
	v_sub_f32_e32 v69, v69, v168
	v_sub_f32_e32 v68, v68, v168
	v_pk_mul_f32 v[68:69], v[166:167], v[68:69] op_sel_hi:[0,1]
	v_pk_mul_f32 v[66:67], v[166:167], v[66:67] op_sel_hi:[0,1]
	v_pk_fma_f32 v[66:67], v[106:107], v[66:67], v[78:79]
	v_pk_fma_f32 v[68:69], v[108:109], v[68:69], v[80:81]
	v_pk_fma_f32 v[10:11], v[10:11], v[82:83], v[66:67]
	v_pk_fma_f32 v[12:13], v[12:13], v[84:85], v[68:69]
	global_store_dwordx4 v183, v[10:13], s[96:97] offset:528
	s_waitcnt vmcnt(15)
	v_sub_f32_e32 v131, v131, v170
	v_sub_f32_e32 v130, v130, v170
	v_sub_f32_e32 v133, v133, v170
	v_sub_f32_e32 v132, v132, v170
	v_pk_mul_f32 v[132:133], v[172:173], v[132:133] op_sel_hi:[0,1]
	v_pk_mul_f32 v[130:131], v[172:173], v[130:131] op_sel_hi:[0,1]
	v_pk_fma_f32 v[130:131], v[106:107], v[130:131], v[78:79]
	v_pk_fma_f32 v[132:133], v[108:109], v[132:133], v[80:81]
	v_pk_fma_f32 v[6:7], v[6:7], v[82:83], v[130:131]
	v_pk_fma_f32 v[8:9], v[8:9], v[84:85], v[132:133]
	global_store_dwordx4 v193, v[6:9], s[96:97] offset:528
	s_waitcnt vmcnt(15)
	v_sub_f32_e32 v119, v119, v162
	v_sub_f32_e32 v118, v118, v162
	v_sub_f32_e32 v121, v121, v162
	v_sub_f32_e32 v120, v120, v162
	v_pk_mul_f32 v[120:121], v[164:165], v[120:121] op_sel_hi:[0,1]
	v_pk_mul_f32 v[118:119], v[164:165], v[118:119] op_sel_hi:[0,1]
	v_pk_fma_f32 v[118:119], v[106:107], v[118:119], v[78:79]
	v_pk_fma_f32 v[120:121], v[108:109], v[120:121], v[80:81]
	v_pk_fma_f32 v[2:3], v[2:3], v[82:83], v[118:119]
	v_pk_fma_f32 v[4:5], v[4:5], v[84:85], v[120:121]
	global_store_dwordx4 v197, v[2:5], s[96:97] offset:528
	s_and_b64 vcc, exec, s[0:1]
	s_mov_b64 s[0:1], -1
	s_cbranch_vccnz .LBB0_235
	s_andn2_b64 vcc, exec, s[8:9]
	s_cbranch_vccnz .LBB0_234
	s_barrier
	s_branch .LBB0_234
